# grid barrier: acquire-side buffer_inv sc1 issued at arrival (beside the arrival atomic) instead of after the release flag
# speedup vs baseline: 1.0262x; 1.0110x over previous
.LBB0_87:
	s_mov_b64 s[8:9], exec
	s_lshl_b32 s3, s67, 8
	v_mbcnt_lo_u32_b32 v3, s8, 0
	s_add_u32 s6, s68, s3
	v_mbcnt_hi_u32_b32 v3, s9, v3
	s_addc_u32 s7, s69, 0
	v_cmp_eq_u32_e32 vcc, 0, v3
	s_and_saveexec_b64 s[10:11], vcc
	s_cbranch_execz .LBB0_89
	s_bcnt1_i32_b64 s3, s[8:9]
	v_mov_b32_e32 v5, 0x1000
	v_mov_b32_e32 v6, s3
	buffer_inv sc1
	global_atomic_add v5, v5, v6, s[6:7] offset:1024 sc0

.LBB0_102:
	s_or_b64 exec, exec, s[10:11]
	s_waitcnt vmcnt(0)
	s_waitcnt vmcnt(0)

.LBB0_120:
	s_or_b64 exec, exec, s[8:9]
	s_mov_b64 s[8:9], exec
	v_mbcnt_lo_u32_b32 v2, s8, 0
	v_mbcnt_hi_u32_b32 v2, s9, v2
	v_cmp_eq_u32_e32 vcc, 0, v2
	s_waitcnt vmcnt(0)
	s_and_saveexec_b64 s[10:11], vcc
	s_cbranch_execz .LBB0_122
	s_bcnt1_i32_b64 s3, s[8:9]
	v_mov_b32_e32 v2, 0x2000
	v_mov_b32_e32 v3, s3
	global_atomic_add v2, v3, s[6:7] offset:1024

.LBB0_415:
	s_mov_b64 s[6:7], exec
	s_lshl_b32 s3, s67, 8
	v_mbcnt_lo_u32_b32 v3, s6, 0
	s_add_u32 s4, s68, s3
	v_mbcnt_hi_u32_b32 v3, s7, v3
	s_addc_u32 s5, s69, 0
	v_cmp_eq_u32_e32 vcc, 0, v3
	s_and_saveexec_b64 s[8:9], vcc
	s_cbranch_execz .LBB0_417
	s_bcnt1_i32_b64 s3, s[6:7]
	v_mov_b32_e32 v5, 0x1000
	v_mov_b32_e32 v6, s3
	buffer_inv sc1
	global_atomic_add v5, v5, v6, s[4:5] offset:1024 sc0

.LBB0_430:
	s_or_b64 exec, exec, s[8:9]
	s_waitcnt vmcnt(0)
	s_waitcnt vmcnt(0)

.LBB0_448:
	s_or_b64 exec, exec, s[6:7]
	s_mov_b64 s[6:7], exec
	v_mbcnt_lo_u32_b32 v2, s6, 0
	v_mbcnt_hi_u32_b32 v2, s7, v2
	v_cmp_eq_u32_e32 vcc, 0, v2
	s_waitcnt vmcnt(0)
	s_and_saveexec_b64 s[8:9], vcc
	s_cbranch_execz .LBB0_450
	s_bcnt1_i32_b64 s3, s[6:7]
	v_mov_b32_e32 v2, 0x2000
	v_mov_b32_e32 v3, s3
	global_atomic_add v2, v3, s[4:5] offset:1024

.LBB0_586:
	s_mov_b64 s[8:9], exec
	s_lshl_b32 s3, s67, 8
	v_mbcnt_lo_u32_b32 v2, s8, 0
	s_add_u32 s6, s68, s3
	v_mbcnt_hi_u32_b32 v2, s9, v2
	s_addc_u32 s7, s69, 0
	v_cmp_eq_u32_e32 vcc, 0, v2
	s_and_saveexec_b64 s[10:11], vcc
	s_cbranch_execz .LBB0_588
	s_bcnt1_i32_b64 s3, s[8:9]
	v_mov_b32_e32 v4, 0x1000
	v_mov_b32_e32 v5, s3
	buffer_inv sc1
	global_atomic_add v4, v4, v5, s[6:7] offset:1024 sc0

.LBB0_619:
	s_or_b64 exec, exec, s[8:9]
	s_mov_b64 s[8:9], exec
	v_mbcnt_lo_u32_b32 v1, s8, 0
	v_mbcnt_hi_u32_b32 v1, s9, v1
	v_cmp_eq_u32_e32 vcc, 0, v1
	s_waitcnt vmcnt(0)
	s_and_saveexec_b64 s[10:11], vcc
	s_cbranch_execz .LBB0_621
	s_bcnt1_i32_b64 s3, s[8:9]
	v_mov_b32_e32 v1, 0x2000
	v_mov_b32_e32 v2, s3
	global_atomic_add v1, v2, s[6:7] offset:1024

.LBB0_661:
	s_mov_b64 s[10:11], exec
	s_lshl_b32 s3, s67, 8
	v_mbcnt_lo_u32_b32 v2, s10, 0
	s_add_u32 s8, s68, s3
	v_mbcnt_hi_u32_b32 v2, s11, v2
	s_addc_u32 s9, s69, 0
	v_cmp_eq_u32_e32 vcc, 0, v2
	s_and_saveexec_b64 s[12:13], vcc
	s_cbranch_execz .LBB0_663
	s_bcnt1_i32_b64 s3, s[10:11]
	v_mov_b32_e32 v4, 0x1000
	v_mov_b32_e32 v5, s3
	buffer_inv sc1
	global_atomic_add v4, v4, v5, s[8:9] offset:1024 sc0

.LBB0_676:
	s_or_b64 exec, exec, s[12:13]
	s_waitcnt vmcnt(0)
	s_waitcnt vmcnt(0)

.LBB0_694:
	s_or_b64 exec, exec, s[10:11]
	s_mov_b64 s[10:11], exec
	v_mbcnt_lo_u32_b32 v1, s10, 0
	v_mbcnt_hi_u32_b32 v1, s11, v1
	v_cmp_eq_u32_e32 vcc, 0, v1
	s_waitcnt vmcnt(0)
	s_and_saveexec_b64 s[12:13], vcc
	s_cbranch_execz .LBB0_696
	s_bcnt1_i32_b64 s3, s[10:11]
	v_mov_b32_e32 v1, 0x2000
	v_mov_b32_e32 v2, s3
	global_atomic_add v1, v2, s[8:9] offset:1024

.LBB0_840:
	s_mov_b64 s[10:11], exec
	s_lshl_b32 s3, s67, 8
	v_mbcnt_lo_u32_b32 v1, s10, 0
	s_add_u32 s8, s68, s3
	v_mbcnt_hi_u32_b32 v1, s11, v1
	s_addc_u32 s9, s69, 0
	v_cmp_eq_u32_e32 vcc, 0, v1
	s_and_saveexec_b64 s[12:13], vcc
	s_cbranch_execz .LBB0_842
	s_bcnt1_i32_b64 s3, s[10:11]
	v_mov_b32_e32 v3, 0x1000
	v_mov_b32_e32 v4, s3
	buffer_inv sc1
	global_atomic_add v3, v3, v4, s[8:9] offset:1024 sc0

.LBB0_873:
	s_or_b64 exec, exec, s[10:11]
	s_mov_b64 s[10:11], exec
	v_mbcnt_lo_u32_b32 v0, s10, 0
	v_mbcnt_hi_u32_b32 v0, s11, v0
	v_cmp_eq_u32_e32 vcc, 0, v0
	s_waitcnt vmcnt(0)
	s_and_saveexec_b64 s[12:13], vcc
	s_cbranch_execz .LBB0_875
	s_bcnt1_i32_b64 s3, s[10:11]
	v_mov_b32_e32 v0, 0x2000
	v_mov_b32_e32 v1, s3
	global_atomic_add v0, v1, s[8:9] offset:1024
